# one static s_setprio 1 for the younger wave half (waves 4-7) during the attention and hyena convolution phases
# baseline (speedup 1.0000x reference)
.LBB0_644:
	s_or_b64 exec, exec, s[0:1]
	s_mov_b64 s[6:7], 0
	s_mov_b64 s[4:5], 0
	s_mov_b64 s[0:1], 0
	s_mov_b64 s[8:9], 0
	v_mov_b32_e32 v2, v0
	s_cmpk_gt_i32 s86, 0x8ff
	s_waitcnt lgkmcnt(0)
	s_barrier
	s_cselect_b32 s99, 1, 0
	v_readfirstlane_b32 s98, v0
	s_bitcmp0_b32 s98, 8
	s_cbranch_scc1 .Lyprio_0
	s_setprio 1

.LBB0_1422:
	s_or_b64 exec, exec, s[0:1]
	s_mov_b64 s[0:1], 0
	s_mov_b64 s[10:11], 0
	s_mov_b64 s[8:9], 0
	s_mov_b64 s[6:7], 0
	v_mov_b32_e32 v3, v0
	s_movk_i32 s2, 0xc08
	s_waitcnt lgkmcnt(0)
	s_barrier
	s_cselect_b32 s99, 1, 0
	v_readfirstlane_b32 s98, v0
	s_bitcmp0_b32 s98, 8
	s_cbranch_scc1 .Lyprio_2
	s_setprio 1
.Lyprio_2:
	s_cmp_lg_u32 s99, 0
	s_mov_b64 s[12:13], 0
	s_nop 0
	v_cmp_gt_i32_e32 vcc, s2, v3
	s_and_saveexec_b64 s[14:15], vcc
	s_cbranch_execz .LBB0_1425
	v_add_u32_e32 v6, 0xfffffe00, v3
	v_mov_b32_e32 v2, 0
	v_lshl_add_u32 v3, v3, 4, 0
	v_add_u32_e32 v7, 0x8080, v3
	v_mov_b32_e32 v3, v2
	v_mov_b32_e32 v4, v2
	v_mov_b32_e32 v5, v2
	s_movk_i32 s2, 0xa07

.LBB0_1698:
	s_or_b64 exec, exec, s[0:1]
	s_add_i32 s2, s3, 0x23ff
	s_ashr_i32 s8, s2, 31
	v_readlane_b32 s4, v250, 32
	s_sub_i32 s9, 0xffffdc01, s3
	s_xor_b32 s8, s8, s4
	s_max_i32 s2, s2, s9
	v_readlane_b32 s4, v250, 33
	s_mul_hi_u32 s9, s2, s4
	v_readlane_b32 s4, v250, 34
	s_mul_i32 s10, s9, s4
	s_sub_i32 s2, s2, s10
	s_add_i32 s10, s9, 1
	s_sub_i32 s11, s2, s4
	s_cmp_ge_u32 s2, s4
	s_cselect_b32 s9, s10, s9
	s_cselect_b32 s2, s11, s2
	s_add_i32 s10, s9, 1
	s_cmp_ge_u32 s2, s4
	s_cselect_b32 s2, s10, s9
	s_xor_b32 s2, s2, s8
	s_sub_i32 s2, s2, s8
	s_mov_b64 s[6:7], 0
	s_mov_b64 s[0:1], 0
	v_mov_b32_e32 v6, v0
	s_cmp_lt_i32 s2, 1
	s_waitcnt lgkmcnt(0)
	s_barrier
	s_setprio 0
	s_cbranch_scc1 .LBB0_1707
	v_readlane_b32 s8, v250, 0
	v_readlane_b32 s10, v250, 2
	v_readlane_b32 s11, v250, 3
	s_add_u32 s6, s10, s6
	s_addc_u32 s7, s11, s7
	v_bfe_u32 v15, v6, 3, 5
	s_add_u32 s6, s6, 0x145e6000
	v_ashrrev_i32_e32 v2, 8, v6
	s_movk_i32 s8, 0x2100
	v_readlane_b32 s4, v250, 27
	v_mul_u32_u24_e32 v3, 0x84, v15
	s_addc_u32 s7, s7, 0
	v_mad_i32_i24 v12, v2, s8, 0
	v_add_u32_e32 v13, s4, v2
	v_mad_i32_i24 v3, v2, s8, v3
	v_lshlrev_b32_e32 v2, 4, v6
	v_and_b32_e32 v2, 0x70, v2
	s_add_u32 s0, s10, s0
	v_readlane_b32 s9, v250, 1
	v_add3_u32 v16, v3, v2, 0
	v_mov_b32_e32 v3, 0
	s_addc_u32 s1, s11, s1
	s_movk_i32 s9, 0xff00
	v_lshl_add_u64 v[4:5], s[0:1], 0, v[2:3]
	s_mov_b64 s[0:1], 0x265e6000
	v_mov_b32_e32 v2, 3
	s_mov_b32 s14, 0
	v_or_b32_sdwa v14, v6, s9 dst_sel:DWORD dst_unused:UNUSED_PAD src0_sel:BYTE_0 src1_sel:DWORD
	v_lshl_add_u64 v[4:5], v[4:5], 0, s[0:1]
	v_lshlrev_b32_sdwa v17, v2, v6 dst_sel:DWORD dst_unused:UNUSED_PAD src0_sel:DWORD src1_sel:BYTE_0
	s_movk_i32 s15, 0x2400
	s_mov_b32 s16, 0x38e38e39
	s_mov_b32 s17, 0x9000
	s_mov_b64 s[8:9], 0x120000
	s_movk_i32 s18, 0x42
	s_mov_b32 s19, 0x5040100
	s_branch .LBB0_1701

.LBB0_2547:
	s_or_b64 exec, exec, s[0:1]
	v_cndmask_b32_e64 v3, 0, 1, s[72:73]
	s_mov_b64 s[10:11], 0
	s_mov_b64 s[8:9], 0
	s_mov_b64 s[0:1], 0
	s_mov_b64 s[12:13], 0
	s_waitcnt lgkmcnt(0)
	v_mov_b32_e32 v2, v0
	v_cmp_ne_u32_e64 s[6:7], 1, v3
	s_andn2_b64 vcc, exec, s[72:73]
	s_barrier
	s_cselect_b32 s99, 1, 0
	v_readfirstlane_b32 s98, v0
	s_bitcmp0_b32 s98, 8
	s_cbranch_scc1 .Lyprio_1
	s_setprio 1

.LBB0_3319:
	s_or_b64 exec, exec, s[0:1]
	s_mov_b64 s[0:1], 0
	s_mov_b64 s[10:11], 0
	s_mov_b64 s[8:9], 0
	s_mov_b64 s[14:15], 0
	v_mov_b32_e32 v3, v0
	s_movk_i32 s2, 0xc08
	s_waitcnt lgkmcnt(0)
	s_barrier
	s_cselect_b32 s99, 1, 0
	v_readfirstlane_b32 s98, v0
	s_bitcmp0_b32 s98, 8
	s_cbranch_scc1 .Lyprio_3
	s_setprio 1

.LBB0_3542:
	s_or_b64 exec, exec, s[0:1]
	s_add_i32 s2, s3, 0x1fff
	s_ashr_i32 s8, s2, 31
	v_readlane_b32 s9, v250, 32
	s_xor_b32 s8, s8, s9
	s_sub_i32 s9, 0xffffe001, s3
	s_max_i32 s2, s2, s9
	v_readlane_b32 s9, v250, 33
	s_mul_hi_u32 s9, s2, s9
	v_readlane_b32 s12, v250, 34
	s_mul_i32 s10, s9, s12
	s_sub_i32 s2, s2, s10
	s_add_i32 s10, s9, 1
	s_sub_i32 s11, s2, s12
	s_cmp_ge_u32 s2, s12
	s_cselect_b32 s9, s10, s9
	s_cselect_b32 s2, s11, s2
	s_add_i32 s10, s9, 1
	s_cmp_ge_u32 s2, s12
	s_cselect_b32 s2, s10, s9
	s_xor_b32 s2, s2, s8
	s_sub_i32 s2, s2, s8
	s_mov_b64 s[6:7], 0
	s_mov_b64 s[0:1], 0
	v_mov_b32_e32 v6, v0
	s_cmp_lt_i32 s2, 1
	s_waitcnt lgkmcnt(0)
	s_barrier
	s_setprio 0
	s_cbranch_scc1 .LBB0_3551
	v_readlane_b32 s8, v250, 0
	v_readlane_b32 s10, v250, 2
	v_readlane_b32 s11, v250, 3
	s_add_u32 s6, s10, s6
	v_readlane_b32 s9, v250, 1
	s_addc_u32 s7, s11, s7
	v_bfe_u32 v15, v6, 3, 5
	s_add_u32 s6, s6, 0x145e6000
	s_waitcnt vmcnt(2)
	v_ashrrev_i32_e32 v2, 8, v6
	s_movk_i32 s8, 0x2100
	v_readlane_b32 s9, v250, 27
	v_mul_u32_u24_e32 v3, 0x84, v15
	s_addc_u32 s7, s7, 0
	v_mad_i32_i24 v12, v2, s8, 0
	v_add_u32_e32 v13, s9, v2
	v_mad_i32_i24 v3, v2, s8, v3
	v_lshlrev_b32_e32 v2, 4, v6
	v_and_b32_e32 v2, 0x70, v2
	s_add_u32 s0, s10, s0
	v_add3_u32 v16, v3, v2, 0
	v_mov_b32_e32 v3, 0
	s_addc_u32 s1, s11, s1
	s_movk_i32 s9, 0xff00
	s_waitcnt vmcnt(0)
	v_lshl_add_u64 v[4:5], s[0:1], 0, v[2:3]
	s_mov_b64 s[0:1], 0x265e6000
	v_mov_b32_e32 v2, 3
	s_mov_b32 s14, 0
	v_or_b32_sdwa v14, v6, s9 dst_sel:DWORD dst_unused:UNUSED_PAD src0_sel:BYTE_0 src1_sel:DWORD
	v_lshl_add_u64 v[4:5], v[4:5], 0, s[0:1]
	v_lshlrev_b32_sdwa v17, v2, v6 dst_sel:DWORD dst_unused:UNUSED_PAD src0_sel:DWORD src1_sel:BYTE_0
	s_movk_i32 s15, 0x2000
	s_mov_b32 s16, 0x9000
	s_mov_b64 s[8:9], 0x120000
	s_movk_i32 s17, 0x42
	s_mov_b32 s18, 0x5040100
	s_branch .LBB0_3545
